# pipelined attention v14: per-MFMA lgkmcnt waits in the MFMA block merged into one wait per group of four
# speedup vs baseline: 1.0270x; 1.0028x over previous
; #define MFMA32(a, b, c) __builtin_amdgcn_mfma_f32_32x32x16_bf16((a), (b), (c), 0, 0, 0)
; DI unsigned pk2(float a, float b) { f32x2 v = {a, b}; return __builtin_bit_cast(unsigned, __builtin_convertvector(v, bfv2)); }
; DI void attn_s(const unsigned char* sK, int tt, int qb, int qs, int sub, int l31, int h,
;                const bf16x8 (&qf)[4], f32x16 (&O)[4], float& m, float& l, bf16x8 (&pb)[4]) {
;     ...
; #pragma unroll
;     for (int k2 = 0; k2 < 2; ++k2)
; #pragma unroll
;         for (int i = 0; i < 16; ++i) st[k2][i] = __builtin_amdgcn_exp2f(st[k2][i]);
;     {
;         const f32x16 sv = st[0] + st[1];
;         const float ps = (((sv[0] + sv[1]) + (sv[2] + sv[3])) + ((sv[4] + sv[5]) + (sv[6] + sv[7]))) + (((sv[8] + sv[9]) + (sv[10] + sv[11])) + ((sv[12] + sv[13]) + (sv[14] + sv[15])));
;         l += ps;
;     }
; #pragma unroll
;     for (int k4 = 0; k4 < 4; ++k4) {
;         const int k2 = k4 >> 1, o8 = 8 * (k4 & 1);
;         u32x4 pk;
;         pk.x = pk2(st[k2][o8 + 0], st[k2][o8 + 1]); pk.y = pk2(st[k2][o8 + 2], st[k2][o8 + 3]);
;         pk.z = pk2(st[k2][o8 + 4], st[k2][o8 + 5]); pk.w = pk2(st[k2][o8 + 6], st[k2][o8 + 7]);
;         pb[k4] = __builtin_bit_cast(bf16x8, pk);
;     }
; DI void attn_pv(const unsigned char* sV, int l31, int h, const bf16x8 (&pb)[4], f32x16 (&O)[4]) {
;     ...
;         for (int d = 0; d < 4; ++d) O[d] = MFMA32(va[d], pb[0], O[d]);
;         __builtin_amdgcn_sched_barrier(0);
; #pragma unroll
;         for (int d = 0; d < 4; ++d) va[d] = *(const bf16x8*)(vb + d * 32 * A_VROWB + 64);
;         __builtin_amdgcn_sched_barrier(0);
; #pragma unroll
;         for (int d = 0; d < 4; ++d) O[d] = MFMA32(vc[d], pb[1], O[d]);
;         __builtin_amdgcn_sched_barrier(0);
; #pragma unroll
;         for (int d = 0; d < 4; ++d) vc[d] = *(const bf16x8*)(vb + d * 32 * A_VROWB + 96);
;         __builtin_amdgcn_sched_barrier(0);
; #pragma unroll
;         for (int d = 0; d < 4; ++d) O[d] = MFMA32(va[d], pb[2], O[d]);
;         __builtin_amdgcn_sched_barrier(0);
; #pragma unroll
;         for (int d = 0; d < 4; ++d) O[d] = MFMA32(vc[d], pb[3], O[d]);
.Lpipe_norescale_l:
	v_exp_f32_e32 v66, v66
	v_exp_f32_e32 v67, v67
	v_exp_f32_e32 v68, v68
	v_exp_f32_e32 v69, v69
	v_exp_f32_e32 v70, v70
	v_exp_f32_e32 v71, v71
	v_exp_f32_e32 v72, v72
	v_exp_f32_e32 v73, v73
	v_exp_f32_e32 v74, v74
	v_exp_f32_e32 v75, v75
	v_exp_f32_e32 v76, v76
	v_exp_f32_e32 v77, v77
	v_exp_f32_e32 v78, v78
	v_exp_f32_e32 v79, v79
	v_exp_f32_e32 v80, v80
	v_exp_f32_e32 v81, v81
	v_cvt_pk_bf16_f32 v216, v82, v83
	v_cvt_pk_bf16_f32 v217, v84, v85
	v_cvt_pk_bf16_f32 v218, v86, v87
	v_cvt_pk_bf16_f32 v219, v88, v89
	v_cvt_pk_bf16_f32 v220, v90, v91
	v_cvt_pk_bf16_f32 v221, v92, v93
	v_cvt_pk_bf16_f32 v222, v94, v95
	v_cvt_pk_bf16_f32 v223, v96, v97
	v_cvt_pk_bf16_f32 v224, v66, v67
	v_cvt_pk_bf16_f32 v225, v68, v69
	v_cvt_pk_bf16_f32 v226, v70, v71
	v_cvt_pk_bf16_f32 v227, v72, v73
	v_cvt_pk_bf16_f32 v228, v74, v75
	v_cvt_pk_bf16_f32 v229, v76, v77
	v_cvt_pk_bf16_f32 v230, v78, v79
	v_cvt_pk_bf16_f32 v231, v80, v81
	v_pk_add_f32 v[68:69], v[84:85], v[68:69]
	v_pk_add_f32 v[66:67], v[82:83], v[66:67]
	v_pk_add_f32 v[72:73], v[88:89], v[72:73]
	v_pk_add_f32 v[70:71], v[86:87], v[70:71]
	v_add_f32_e32 v66, v66, v67
	v_add_f32_e32 v67, v68, v69
	v_add_f32_e32 v66, v66, v67
	v_add_f32_e32 v67, v70, v71
	v_add_f32_e32 v68, v72, v73
	v_pk_add_f32 v[76:77], v[92:93], v[76:77]
	v_pk_add_f32 v[74:75], v[90:91], v[74:75]
	v_add_f32_e32 v67, v67, v68
	v_pk_add_f32 v[80:81], v[96:97], v[80:81]
	v_pk_add_f32 v[78:79], v[94:95], v[78:79]
	v_add_f32_e32 v66, v66, v67
	v_add_f32_e32 v67, v74, v75
	v_add_f32_e32 v68, v76, v77
	v_add_f32_e32 v67, v67, v68
	v_add_f32_e32 v68, v78, v79
	v_add_f32_e32 v69, v80, v81
	v_add_f32_e32 v68, v68, v69
	v_add_f32_e32 v67, v67, v68
	v_add_f32_e32 v66, v66, v67
	v_add_f32_e32 v1, v1, v66
	v_add_u32_e32 v158, 64, v158
	v_lshl_add_u64 v[144:145], v[144:145], 0, s[90:91]
	v_lshl_add_u64 v[142:143], v[142:143], 0, s[88:89]
	v_lshl_add_u64 v[184:185], v[144:145], 0, s[92:93]
	v_add_co_u32_e32 v238, vcc, 0x80000, v142
	s_mul_i32 s98, s7, 0x8c00
	s_nop 0
	v_addc_co_u32_e32 v239, vcc, 0, v143, vcc
	v_add3_u32 v237, s98, v155, v154
	s_add_i32 s4, s7, 1
	s_cmp_lg_u32 s7, 2
	s_cselect_b32 s4, s4, 0
	s_mul_i32 s4, s4, 0x8c00
	v_add3_u32 v232, s4, v140, v139
	v_add3_u32 v233, s4, v140, v141
	v_add3_u32 v234, s4, v150, v151
	v_add_u32_e32 v235, v234, v153
	v_add_u32_e32 v234, v234, v152
	v_add_u32_e32 v235, 0x4000, v235
	v_add_u32_e32 v234, 0x4000, v234
	s_mov_b32 s13, s7
	s_add_i32 s4, s7, 1
	s_cmp_lg_u32 s7, 2
	s_cselect_b32 s7, s4, 0
	s_add_i32 s12, s12, 1
	s_cmp_eq_u32 s11, s12
	s_cbranch_scc1 .Lpipe_final
	s_barrier
	s_setprio 1
	ds_read_b128 v[160:163], v237
	ds_read_b128 v[164:167], v237 offset:32
	ds_read_b128 v[168:171], v237 offset:8704
	ds_read_b128 v[196:199], v237 offset:8736
	s_waitcnt lgkmcnt(8)
	v_mfma_f32_32x32x16_bf16 v[50:65], v[172:175], v[216:219], v[50:65]
	ds_read_b128 v[172:175], v237 offset:64
	v_mfma_f32_32x32x16_bf16 v[34:49], v[176:179], v[216:219], v[34:49]
	ds_read_b128 v[176:179], v237 offset:96
	v_mfma_f32_32x32x16_bf16 v[18:33], v[180:183], v[216:219], v[18:33]
	ds_read_b128 v[180:183], v237 offset:8768
	v_mfma_f32_32x32x16_bf16 v[2:17], v[192:195], v[216:219], v[2:17]
	ds_read_b128 v[192:195], v237 offset:8800
	s_waitcnt lgkmcnt(8)
	v_mfma_f32_32x32x16_bf16 v[50:65], v[200:203], v[220:223], v[50:65]
	ds_read_b128 v[200:203], v191 offset:17472
	v_mfma_f32_32x32x16_bf16 v[34:49], v[204:207], v[220:223], v[34:49]
	ds_read_b128 v[204:207], v191 offset:22080
	v_mfma_f32_32x32x16_bf16 v[18:33], v[208:211], v[220:223], v[18:33]
	ds_read_b128 v[208:211], v191 offset:26688
	v_mfma_f32_32x32x16_bf16 v[2:17], v[212:215], v[220:223], v[2:17]
	ds_read_b128 v[212:215], v191 offset:31296
	s_waitcnt lgkmcnt(8)
	v_mfma_f32_32x32x16_bf16 v[82:97], v[160:163], v[100:103], v[240:255]
	ds_read_b128 v[160:163], v191 offset:17504
	v_mfma_f32_32x32x16_bf16 v[66:81], v[168:171], v[100:103], v[240:255]
	ds_read_b128 v[168:171], v191 offset:26720
	v_mfma_f32_32x32x16_bf16 v[82:97], v[164:167], v[104:107], v[82:97]
	ds_read_b128 v[164:167], v191 offset:22112
	v_mfma_f32_32x32x16_bf16 v[66:81], v[196:199], v[104:107], v[66:81]
	ds_read_b128 v[196:199], v191 offset:31328
	s_waitcnt lgkmcnt(8)
	v_mfma_f32_32x32x16_bf16 v[82:97], v[172:175], v[108:111], v[82:97]
	s_waitcnt vmcnt(3)
	ds_write_b128 v232, v[116:119]
	v_mfma_f32_32x32x16_bf16 v[66:81], v[180:183], v[108:111], v[66:81]
	s_waitcnt vmcnt(2)
	ds_write_b128 v233, v[120:123]
	v_mfma_f32_32x32x16_bf16 v[82:97], v[176:179], v[112:115], v[82:97]
	s_waitcnt vmcnt(1)
	ds_write2_b64 v234, v[124:125], v[126:127] offset0:128 offset1:130
	v_mfma_f32_32x32x16_bf16 v[66:81], v[192:195], v[112:115], v[66:81]
	s_waitcnt vmcnt(0)
	ds_write2_b64 v235, v[128:129], v[130:131] offset0:128 offset1:130
	s_add_i32 s14, s12, 0x43
	s_cmp_ge_i32 s14, s6
	s_cbranch_scc1 .Lpipe_k2_nopf
	s_waitcnt lgkmcnt(8)
	v_mfma_f32_32x32x16_bf16 v[50:65], v[200:203], v[224:227], v[50:65]
	global_load_dwordx4 v[116:119], v[144:145], off
	v_mfma_f32_32x32x16_bf16 v[34:49], v[204:207], v[224:227], v[34:49]
	global_load_dwordx4 v[120:123], v[184:185], off
	v_mfma_f32_32x32x16_bf16 v[18:33], v[208:211], v[224:227], v[18:33]
	global_load_dwordx4 v[124:127], v[142:143], off
	v_mfma_f32_32x32x16_bf16 v[2:17], v[212:215], v[224:227], v[2:17]
	global_load_dwordx4 v[128:131], v[238:239], off
	s_branch .Lpipe_k3
.Lpipe_k2_nopf:
	s_waitcnt lgkmcnt(8)
	v_mfma_f32_32x32x16_bf16 v[50:65], v[200:203], v[224:227], v[50:65]
	v_mfma_f32_32x32x16_bf16 v[34:49], v[204:207], v[224:227], v[34:49]
	v_mfma_f32_32x32x16_bf16 v[18:33], v[208:211], v[224:227], v[18:33]
	v_mfma_f32_32x32x16_bf16 v[2:17], v[212:215], v[224:227], v[2:17]
.Lpipe_k3:
	s_waitcnt lgkmcnt(4)
	v_mfma_f32_32x32x16_bf16 v[50:65], v[160:163], v[228:231], v[50:65]
	v_mfma_f32_32x32x16_bf16 v[34:49], v[164:167], v[228:231], v[34:49]
	v_mfma_f32_32x32x16_bf16 v[18:33], v[168:171], v[228:231], v[18:33]
	v_mfma_f32_32x32x16_bf16 v[2:17], v[196:199], v[228:231], v[2:17]
	s_setprio 0
	s_waitcnt lgkmcnt(0)
	s_barrier
	s_branch .Lpipe_loop
